# first norm phase gated only by the 48 layer-0 modulation items (layer-1 items are published by the next grid barrier)
# speedup vs baseline: 1.0032x; 1.0032x over previous
.Lmd_done:
	s_waitcnt vmcnt(0)
	s_barrier
	s_cmp_lg_u32 s12, 0
	s_cbranch_scc1 .Lmd_nosig
	v_cmp_eq_u32_e32 vcc, 0, v143
	s_and_saveexec_b64 s[24:25], vcc
	s_cbranch_execz .Lmd_sig
	buffer_wbl2 sc1
	s_waitcnt vmcnt(0)
	s_add_u32 s10, s50, 0x1aa5d080
	s_addc_u32 s11, s51, 0
	v_mov_b32_e32 v2, 0
	v_mov_b32_e32 v3, 1
	global_atomic_add v2, v3, s[10:11]
	s_waitcnt vmcnt(0)
.Lmd_sig:
	s_or_b64 exec, exec, s[24:25]
.Lmd_nosig:
	s_branch .LBB0_14
.Lwp_entry:
	s_mov_b64 s[84:85], s[0:1]
	s_mov_b32 s86, s18
	s_mov_b32 s87, s19
	s_mov_b64 s[88:89], s[22:23]
	s_mov_b64 s[92:93], s[26:27]
	s_mov_b64 s[94:95], s[30:31]
	v_mov_b32_e32 v120, v0
	v_mov_b32_e32 v121, v1
	v_mov_b32_e32 v122, v57
	s_load_dwordx8 s[52:59], s[0:1], 0x40
	s_waitcnt lgkmcnt(0)
	s_waitcnt vmcnt(0)
	v_and_b32_e32 v105, 15, v143
	v_bfe_u32 v106, v143, 4, 2
	v_lshlrev_b32_e32 v107, 5, v106
	v_mov_b32_e32 v108, 0
	v_mov_b32_e32 v109, 0
	v_mov_b32_e32 v110, 0
	v_mov_b32_e32 v111, 0
	v_readfirstlane_b32 s0, v143
	s_lshr_b32 s0, s0, 6
	v_readlane_b32 s1, v253, 0
	s_sub_u32 s1, s1, 96
	s_lshl_b32 s1, s1, 3
	s_add_i32 s21, s1, s0
	s_movk_i32 s19, 1
	s_mul_i32 s34, s21, 13
	s_add_u32 s35, s34, 13
	s_min_u32 s35, s35, 16640
	s_max_u32 s0, s34, 0
	s_min_u32 s1, s35, 5632
	s_cmp_lt_u32 s0, s1
	s_cbranch_scc0 .Lwp_ret_0
	s_sub_u32 s33, s0, 0
	s_sub_u32 s28, s1, 0
	v_readlane_b32 s4, v253, 15
	v_readlane_b32 s5, v253, 16
	s_add_u32 s6, s50, 0
	s_addc_u32 s7, s51, 0
	s_mov_b32 s8, 10368
	s_mov_b32 s9, 2048
	s_mov_b32 s10, 176
	s_mov_b32 s11, s28
	s_mov_b32 s12, 0x1745d18
	s_mov_b32 s13, 0
	s_mov_b32 s16, 162
	s_mov_b64 s[14:15], 0
	s_mov_b32 s20, 0
	s_branch .Lwp_mat

.Lmr_spin:
	global_load_dword v3, v0, s[10:11] sc1
	s_waitcnt vmcnt(0)
	v_cmp_gt_u32_e32 vcc, 0x30, v3
	s_cbranch_vccz .Lmr_ready
	s_sleep 1
	s_branch .Lmr_spin
